# prompt residual epilogue: accumulator permutation split in two halves, the second half overlapping the second batch of residual-row loads
# baseline (speedup 1.0000x reference)
.LBB0_308:
	v_readlane_b32 s30, v253, 41
	v_readlane_b32 s31, v253, 29
	s_lshl_b32 s38, s30, 1
	s_cmp_eq_u32 s31, 8
	s_cselect_b32 s31, 1, 0
	s_add_i32 s38, s38, s31
	s_ashr_i32 s25, s76, 5
	s_mul_i32 s25, s25, 0x18000
	s_add_u32 s36, s18, s25
	s_addc_u32 s37, s19, 0
	v_lshlrev_b64 v[226:227], 2, v[194:195]
	v_ashrrev_i32_e32 v193, 31, v192
	v_lshlrev_b64 v[228:229], 12, v[192:193]
	v_lshl_add_u64 v[244:245], s[36:37], 0, v[226:227]
	global_load_dwordx4 v[198:201], v[244:245], off offset:0
	global_load_dwordx4 v[202:205], v[244:245], off offset:64
	global_load_dwordx4 v[210:213], v[244:245], off offset:512
	global_load_dwordx4 v[214:217], v[244:245], off offset:576
	v_lshl_add_u64 v[242:243], s[12:13], 0, v[226:227]
	v_lshl_add_u64 v[242:243], v[242:243], 0, v[228:229]
	s_mov_b32 s31, 0
	s_mov_b32 s30, 0x0
	v_lshl_add_u64 v[246:247], v[242:243], 0, s[30:31]
	global_load_dwordx4 v[134:137], v[246:247], off offset:0
	global_load_dwordx4 v[138:141], v[246:247], off offset:64
	global_load_dwordx4 v[142:145], v[246:247], off offset:512
	global_load_dwordx4 v[146:149], v[246:247], off offset:576
	s_mov_b32 s30, 0x10000
	v_lshl_add_u64 v[246:247], v[242:243], 0, s[30:31]
	global_load_dwordx4 v[150:153], v[246:247], off offset:0
	global_load_dwordx4 v[154:157], v[246:247], off offset:64
	global_load_dwordx4 v[158:161], v[246:247], off offset:512
	global_load_dwordx4 v[162:165], v[246:247], off offset:576
	s_mov_b32 s30, 0x20000
	v_lshl_add_u64 v[246:247], v[242:243], 0, s[30:31]
	global_load_dwordx4 v[166:169], v[246:247], off offset:0
	global_load_dwordx4 v[170:173], v[246:247], off offset:64
	global_load_dwordx4 v[174:177], v[246:247], off offset:512
	global_load_dwordx4 v[178:181], v[246:247], off offset:576
	s_mov_b32 s30, 0x30000
	v_lshl_add_u64 v[246:247], v[242:243], 0, s[30:31]
	global_load_dwordx4 v[182:185], v[246:247], off offset:0
	global_load_dwordx4 v[186:189], v[246:247], off offset:64
	global_load_dwordx4 v[190:193], v[246:247], off offset:512
	global_load_dwordx4 v[194:197], v[246:247], off offset:576
	ds_bpermute_b32 v70, v222, v70
	ds_bpermute_b32 v71, v222, v71
	ds_bpermute_b32 v72, v222, v72
	ds_bpermute_b32 v73, v222, v73
	ds_bpermute_b32 v74, v222, v74
	ds_bpermute_b32 v75, v222, v75
	ds_bpermute_b32 v76, v222, v76
	ds_bpermute_b32 v77, v222, v77
	ds_bpermute_b32 v78, v222, v78
	ds_bpermute_b32 v79, v222, v79
	ds_bpermute_b32 v80, v222, v80
	ds_bpermute_b32 v81, v222, v81
	ds_bpermute_b32 v82, v222, v82
	ds_bpermute_b32 v83, v222, v83
	ds_bpermute_b32 v84, v222, v84
	ds_bpermute_b32 v85, v222, v85
	s_waitcnt lgkmcnt(8)
	ds_bpermute_b32 v86, v222, v86
	ds_bpermute_b32 v87, v222, v87
	ds_bpermute_b32 v88, v222, v88
	ds_bpermute_b32 v89, v222, v89
	ds_bpermute_b32 v90, v222, v90
	ds_bpermute_b32 v91, v222, v91
	ds_bpermute_b32 v92, v222, v92
	ds_bpermute_b32 v93, v222, v93
	s_waitcnt lgkmcnt(8)
	ds_bpermute_b32 v94, v222, v94
	ds_bpermute_b32 v95, v222, v95
	ds_bpermute_b32 v96, v222, v96
	ds_bpermute_b32 v97, v222, v97
	ds_bpermute_b32 v98, v222, v98
	ds_bpermute_b32 v99, v222, v99
	ds_bpermute_b32 v100, v222, v100
	ds_bpermute_b32 v101, v222, v101
	s_waitcnt lgkmcnt(8)
	ds_bpermute_b32 v102, v222, v102
	ds_bpermute_b32 v103, v222, v103
	ds_bpermute_b32 v104, v222, v104
	ds_bpermute_b32 v105, v222, v105
	ds_bpermute_b32 v106, v222, v106
	ds_bpermute_b32 v107, v222, v107
	ds_bpermute_b32 v108, v222, v108
	ds_bpermute_b32 v109, v222, v109
	s_waitcnt lgkmcnt(8)
	ds_bpermute_b32 v110, v222, v110
	ds_bpermute_b32 v111, v222, v111
	ds_bpermute_b32 v112, v222, v112
	ds_bpermute_b32 v113, v222, v113
	ds_bpermute_b32 v114, v222, v114
	ds_bpermute_b32 v115, v222, v115
	ds_bpermute_b32 v116, v222, v116
	ds_bpermute_b32 v117, v222, v117
	s_waitcnt lgkmcnt(8)
	ds_bpermute_b32 v118, v222, v118
	ds_bpermute_b32 v119, v222, v119
	ds_bpermute_b32 v120, v222, v120
	ds_bpermute_b32 v121, v222, v121
	ds_bpermute_b32 v122, v222, v122
	ds_bpermute_b32 v123, v222, v123
	ds_bpermute_b32 v124, v222, v124
	ds_bpermute_b32 v125, v222, v125
	s_waitcnt lgkmcnt(8)
	ds_bpermute_b32 v126, v222, v126
	ds_bpermute_b32 v127, v222, v127
	ds_bpermute_b32 v128, v222, v128
	ds_bpermute_b32 v129, v222, v129
	ds_bpermute_b32 v130, v222, v130
	ds_bpermute_b32 v131, v222, v131
	ds_bpermute_b32 v132, v222, v132
	ds_bpermute_b32 v133, v222, v133
	s_waitcnt lgkmcnt(0)
	s_waitcnt vmcnt(0)
	v_pk_fma_f32 v[130:131], v[130:131], v[198:199], v[134:135]
	v_pk_fma_f32 v[132:133], v[132:133], v[200:201], v[136:137]
	v_pk_fma_f32 v[126:127], v[126:127], v[202:203], v[138:139]
	v_pk_fma_f32 v[128:129], v[128:129], v[204:205], v[140:141]
	v_pk_fma_f32 v[122:123], v[122:123], v[210:211], v[142:143]
	v_pk_fma_f32 v[124:125], v[124:125], v[212:213], v[144:145]
	v_pk_fma_f32 v[118:119], v[118:119], v[214:215], v[146:147]
	v_pk_fma_f32 v[120:121], v[120:121], v[216:217], v[148:149]
	v_pk_fma_f32 v[114:115], v[114:115], v[198:199], v[150:151]
	v_pk_fma_f32 v[116:117], v[116:117], v[200:201], v[152:153]
	v_pk_fma_f32 v[110:111], v[110:111], v[202:203], v[154:155]
	v_pk_fma_f32 v[112:113], v[112:113], v[204:205], v[156:157]
	v_pk_fma_f32 v[106:107], v[106:107], v[210:211], v[158:159]
	v_pk_fma_f32 v[108:109], v[108:109], v[212:213], v[160:161]
	v_pk_fma_f32 v[102:103], v[102:103], v[214:215], v[162:163]
	v_pk_fma_f32 v[104:105], v[104:105], v[216:217], v[164:165]
	v_pk_fma_f32 v[98:99], v[98:99], v[198:199], v[166:167]
	v_pk_fma_f32 v[100:101], v[100:101], v[200:201], v[168:169]
	v_pk_fma_f32 v[94:95], v[94:95], v[202:203], v[170:171]
	v_pk_fma_f32 v[96:97], v[96:97], v[204:205], v[172:173]
	v_pk_fma_f32 v[90:91], v[90:91], v[210:211], v[174:175]
	v_pk_fma_f32 v[92:93], v[92:93], v[212:213], v[176:177]
	v_pk_fma_f32 v[86:87], v[86:87], v[214:215], v[178:179]
	v_pk_fma_f32 v[88:89], v[88:89], v[216:217], v[180:181]
	v_pk_fma_f32 v[82:83], v[82:83], v[198:199], v[182:183]
	v_pk_fma_f32 v[84:85], v[84:85], v[200:201], v[184:185]
	v_pk_fma_f32 v[78:79], v[78:79], v[202:203], v[186:187]
	v_pk_fma_f32 v[80:81], v[80:81], v[204:205], v[188:189]
	v_pk_fma_f32 v[74:75], v[74:75], v[210:211], v[190:191]
	v_pk_fma_f32 v[76:77], v[76:77], v[212:213], v[192:193]
	v_pk_fma_f32 v[70:71], v[70:71], v[214:215], v[194:195]
	v_pk_fma_f32 v[72:73], v[72:73], v[216:217], v[196:197]
	s_mov_b32 s30, 0x80000
	v_lshl_add_u64 v[246:247], v[242:243], 0, s[30:31]
	global_load_dwordx4 v[134:137], v[246:247], off offset:0
	global_load_dwordx4 v[138:141], v[246:247], off offset:64
	global_load_dwordx4 v[142:145], v[246:247], off offset:512
	global_load_dwordx4 v[146:149], v[246:247], off offset:576
	s_mov_b32 s30, 0x90000
	v_lshl_add_u64 v[246:247], v[242:243], 0, s[30:31]
	global_load_dwordx4 v[150:153], v[246:247], off offset:0
	global_load_dwordx4 v[154:157], v[246:247], off offset:64
	global_load_dwordx4 v[158:161], v[246:247], off offset:512
	global_load_dwordx4 v[162:165], v[246:247], off offset:576
	s_mov_b32 s30, 0xa0000
	v_lshl_add_u64 v[246:247], v[242:243], 0, s[30:31]
	global_load_dwordx4 v[166:169], v[246:247], off offset:0
	global_load_dwordx4 v[170:173], v[246:247], off offset:64
	global_load_dwordx4 v[174:177], v[246:247], off offset:512
	global_load_dwordx4 v[178:181], v[246:247], off offset:576
	s_mov_b32 s30, 0xb0000
	v_lshl_add_u64 v[246:247], v[242:243], 0, s[30:31]
	global_load_dwordx4 v[182:185], v[246:247], off offset:0
	global_load_dwordx4 v[186:189], v[246:247], off offset:64
	global_load_dwordx4 v[190:193], v[246:247], off offset:512
	global_load_dwordx4 v[194:197], v[246:247], off offset:576
	ds_bpermute_b32 v6, v222, v6
	ds_bpermute_b32 v7, v222, v7
	ds_bpermute_b32 v8, v222, v8
	ds_bpermute_b32 v9, v222, v9
	ds_bpermute_b32 v10, v222, v10
	ds_bpermute_b32 v11, v222, v11
	ds_bpermute_b32 v12, v222, v12
	ds_bpermute_b32 v13, v222, v13
	ds_bpermute_b32 v14, v222, v14
	ds_bpermute_b32 v15, v222, v15
	ds_bpermute_b32 v16, v222, v16
	ds_bpermute_b32 v17, v222, v17
	ds_bpermute_b32 v18, v222, v18
	ds_bpermute_b32 v19, v222, v19
	ds_bpermute_b32 v20, v222, v20
	ds_bpermute_b32 v21, v222, v21
	s_waitcnt lgkmcnt(8)
	ds_bpermute_b32 v22, v222, v22
	ds_bpermute_b32 v23, v222, v23
	ds_bpermute_b32 v24, v222, v24
	ds_bpermute_b32 v25, v222, v25
	ds_bpermute_b32 v26, v222, v26
	ds_bpermute_b32 v27, v222, v27
	ds_bpermute_b32 v28, v222, v28
	ds_bpermute_b32 v29, v222, v29
	s_waitcnt lgkmcnt(8)
	ds_bpermute_b32 v30, v222, v30
	ds_bpermute_b32 v31, v222, v31
	ds_bpermute_b32 v32, v222, v32
	ds_bpermute_b32 v33, v222, v33
	ds_bpermute_b32 v34, v222, v34
	ds_bpermute_b32 v35, v222, v35
	ds_bpermute_b32 v36, v222, v36
	ds_bpermute_b32 v37, v222, v37
	s_waitcnt lgkmcnt(8)
	ds_bpermute_b32 v38, v222, v38
	ds_bpermute_b32 v39, v222, v39
	ds_bpermute_b32 v40, v222, v40
	ds_bpermute_b32 v41, v222, v41
	ds_bpermute_b32 v42, v222, v42
	ds_bpermute_b32 v43, v222, v43
	ds_bpermute_b32 v44, v222, v44
	ds_bpermute_b32 v45, v222, v45
	s_waitcnt lgkmcnt(8)
	ds_bpermute_b32 v46, v222, v46
	ds_bpermute_b32 v47, v222, v47
	ds_bpermute_b32 v48, v222, v48
	ds_bpermute_b32 v49, v222, v49
	ds_bpermute_b32 v50, v222, v50
	ds_bpermute_b32 v51, v222, v51
	ds_bpermute_b32 v52, v222, v52
	ds_bpermute_b32 v53, v222, v53
	s_waitcnt lgkmcnt(8)
	ds_bpermute_b32 v54, v222, v54
	ds_bpermute_b32 v55, v222, v55
	ds_bpermute_b32 v56, v222, v56
	ds_bpermute_b32 v57, v222, v57
	ds_bpermute_b32 v58, v222, v58
	ds_bpermute_b32 v59, v222, v59
	ds_bpermute_b32 v60, v222, v60
	ds_bpermute_b32 v61, v222, v61
	s_waitcnt lgkmcnt(8)
	ds_bpermute_b32 v62, v222, v62
	ds_bpermute_b32 v63, v222, v63
	ds_bpermute_b32 v64, v222, v64
	ds_bpermute_b32 v65, v222, v65
	ds_bpermute_b32 v66, v222, v66
	ds_bpermute_b32 v67, v222, v67
	ds_bpermute_b32 v68, v222, v68
	ds_bpermute_b32 v69, v222, v69
	s_waitcnt lgkmcnt(0)
	s_waitcnt vmcnt(0)
	v_pk_fma_f32 v[66:67], v[66:67], v[198:199], v[134:135]
	v_pk_fma_f32 v[68:69], v[68:69], v[200:201], v[136:137]
	v_pk_fma_f32 v[62:63], v[62:63], v[202:203], v[138:139]
	v_pk_fma_f32 v[64:65], v[64:65], v[204:205], v[140:141]
	v_pk_fma_f32 v[58:59], v[58:59], v[210:211], v[142:143]
	v_pk_fma_f32 v[60:61], v[60:61], v[212:213], v[144:145]
	v_pk_fma_f32 v[54:55], v[54:55], v[214:215], v[146:147]
	v_pk_fma_f32 v[56:57], v[56:57], v[216:217], v[148:149]
	v_pk_fma_f32 v[50:51], v[50:51], v[198:199], v[150:151]
	v_pk_fma_f32 v[52:53], v[52:53], v[200:201], v[152:153]
	v_pk_fma_f32 v[46:47], v[46:47], v[202:203], v[154:155]
	v_pk_fma_f32 v[48:49], v[48:49], v[204:205], v[156:157]
	v_pk_fma_f32 v[42:43], v[42:43], v[210:211], v[158:159]
	v_pk_fma_f32 v[44:45], v[44:45], v[212:213], v[160:161]
	v_pk_fma_f32 v[38:39], v[38:39], v[214:215], v[162:163]
	v_pk_fma_f32 v[40:41], v[40:41], v[216:217], v[164:165]
	v_pk_fma_f32 v[34:35], v[34:35], v[198:199], v[166:167]
	v_pk_fma_f32 v[36:37], v[36:37], v[200:201], v[168:169]
	v_pk_fma_f32 v[30:31], v[30:31], v[202:203], v[170:171]
	v_pk_fma_f32 v[32:33], v[32:33], v[204:205], v[172:173]
	v_pk_fma_f32 v[26:27], v[26:27], v[210:211], v[174:175]
	v_pk_fma_f32 v[28:29], v[28:29], v[212:213], v[176:177]
	v_pk_fma_f32 v[22:23], v[22:23], v[214:215], v[178:179]
	v_pk_fma_f32 v[24:25], v[24:25], v[216:217], v[180:181]
	v_pk_fma_f32 v[18:19], v[18:19], v[198:199], v[182:183]
	v_pk_fma_f32 v[20:21], v[20:21], v[200:201], v[184:185]
	v_pk_fma_f32 v[14:15], v[14:15], v[202:203], v[186:187]
	v_pk_fma_f32 v[16:17], v[16:17], v[204:205], v[188:189]
	v_pk_fma_f32 v[10:11], v[10:11], v[210:211], v[190:191]
	v_pk_fma_f32 v[12:13], v[12:13], v[212:213], v[192:193]
	v_pk_fma_f32 v[6:7], v[6:7], v[214:215], v[194:195]
	v_pk_fma_f32 v[8:9], v[8:9], v[216:217], v[196:197]
	s_cmp_eq_u32 s38, 7
	s_cbranch_scc1 .Lrn_final_p
	s_and_b32 s25, s38, 1
	s_lshr_b32 s30, s38, 1
	s_cmp_eq_u32 s25, 0
	s_cbranch_scc1 .Lrn_ffn_p
	s_add_i32 s30, s30, 1
	s_movk_i32 s25, 0x48
	s_mul_i32 s31, s30, 0x6000
	s_branch .Lrn_p_done
